# attention: partialSM exps interleaved into last PV MFMA group on the nomax path
# speedup vs baseline: 1.0004x; 1.0004x over previous
; template <bool FIRST = false>
; __device__ __forceinline__ void partialSM(f32x16& p0, f32x16& p1, float& m_reg, float& mn, float& alpha, const bool nomax) {
;   if (nomax) { mn = 0.f; alpha = 1.f;
; #pragma unroll
;     for (int r = 0; r < 16; ++r) p0[r] = __builtin_amdgcn_exp2f(p0[r]);
;     return; }
;   float pmax = p0[0];
; #pragma unroll
;   for (int r = 1; r < 16; ++r) pmax = fmaxf(pmax, p0[r]);
; #pragma unroll
;   for (int r = 0; r < 16; ++r) pmax = fmaxf(pmax, p1[r]);
;   { auto rr = __builtin_amdgcn_permlane32_swap(__float_as_uint(pmax), __float_as_uint(pmax), false, false); pmax = fmaxf(__uint_as_float(rr[0]), __uint_as_float(rr[1])); }
;   if (FIRST) { m_reg = (__builtin_fabsf(pmax) <= THRL) ? 0.f : pmax; mn = m_reg; alpha = 1.f; }
;   else if (__builtin_expect(__all(pmax - m_reg <= THRL), 1)) { mn = m_reg; alpha = 1.f; }
;   else { mn = fmaxf(m_reg, pmax); alpha = __builtin_amdgcn_exp2f(m_reg - mn); m_reg = mn; }
;   if (__builtin_expect(__any(mn != 0.f), 0)) {
; #pragma unroll
;     for (int r = 0; r < 16; ++r) { p0[r] = p0[r] - mn; p1[r] = p1[r] - mn; } }
; #pragma unroll
;   for (int r = 0; r < 16; ++r) p0[r] = __builtin_amdgcn_exp2f(p0[r]);
; }
; __device__ __forceinline__ void finishSM(f32x16& p0, f32x16& p1, float alpha, float& l_reg, bf16x8& pa0, bf16x8& pa1, bf16x8& pa2, bf16x8& pa3) {
; #pragma unroll
;   for (int r = 0; r < 16; ++r) p1[r] = __builtin_amdgcn_exp2f(p1[r]);
;   typedef float f32x8_ __attribute__((ext_vector_type(8))); typedef float f32x2_ __attribute__((ext_vector_type(2)));
;   const f32x16 s16_ = p0 + p1; const f32x8_ s8_ = s16_.lo + s16_.hi; const f32x4 s4_ = s8_.lo + s8_.hi; const f32x2_ s2_ = s4_.lo + s4_.hi;
;   float ps = s2_.x + s2_.y;
;   { auto rr = __builtin_amdgcn_permlane32_swap(__float_as_uint(ps), __float_as_uint(ps), false, false); ps = __uint_as_float(rr[0]) + __uint_as_float(rr[1]); }
;   l_reg = l_reg * alpha + ps;
;     ...
;   A128_PK4(p0, 0, pa0); A128_PK4(p0, 8, pa1); A128_PK4(p1, 0, pa2); A128_PK4(p1, 8, pa3);
;     ...
; }
; __device__ __forceinline__ void qkt(f32x16& p0, f32x16& p1, const char* Ks, const bf16x8* qr, int r32, int hi) {
; #pragma unroll
;   for (int i = 0; i < 16; ++i) { p0[i] = 0.f; p1[i] = 0.f; }
; #pragma unroll
;   for (int d0 = 0; d0 < 4; ++d0) { const int cb = (d0 * 16 + hi * 8) * 2;
;     const bf16x8 b0 = *reinterpret_cast<const bf16x8*>(Ks + A128_KSWZ(r32, cb));
.LBB0_1110:
	ds_read_b128 v[2:5], v204 offset:40960
	ds_read_b128 v[6:9], v204 offset:45056
	ds_read_b128 v[232:235], v205 offset:40960
	ds_read_b128 v[236:239], v205 offset:45056
	ds_read_b128 v[240:243], v192 offset:40960
	ds_read_b128 v[244:247], v192 offset:45056
	v_exp_f32_e32 v10, v88
	v_exp_f32_e32 v11, v89
	v_exp_f32_e32 v12, v90
	s_waitcnt lgkmcnt(5)
	v_mfma_f32_32x32x16_bf16 v[112:127], v[2:5], v[140:143], 0
	v_exp_f32_e32 v13, v91
	v_exp_f32_e32 v194, v92
	v_exp_f32_e32 v195, v93
	v_exp_f32_e32 v196, v94
	v_exp_f32_e32 v197, v95
	v_pk_add_f32 v[14:15], v[168:169], v[12:13]
	v_pk_add_f32 v[90:91], v[164:165], v[194:195]
	s_waitcnt lgkmcnt(4)
	v_mfma_f32_32x32x16_bf16 v[96:111], v[6:9], v[140:143], 0
	ds_read_b128 v[2:5], v193 offset:40960
	ds_read_b128 v[6:9], v193 offset:45056
	s_waitcnt lgkmcnt(5)
	v_mfma_f32_32x32x16_bf16 v[112:127], v[232:235], v[136:139], v[112:127]
	s_waitcnt lgkmcnt(4)
	v_mfma_f32_32x32x16_bf16 v[96:111], v[236:239], v[136:139], v[96:111]
	s_waitcnt lgkmcnt(3)
	v_mfma_f32_32x32x16_bf16 v[112:127], v[240:243], v[132:135], v[112:127]
	s_waitcnt lgkmcnt(2)
	v_mfma_f32_32x32x16_bf16 v[96:111], v[244:247], v[132:135], v[96:111]
	s_waitcnt lgkmcnt(1)
	v_mfma_f32_32x32x16_bf16 v[112:127], v[2:5], v[128:131], v[112:127]
	v_exp_f32_e32 v2, v80
	v_exp_f32_e32 v3, v81
	v_exp_f32_e32 v4, v82
	v_exp_f32_e32 v5, v83
	v_pk_add_f32 v[82:83], v[162:163], v[196:197]
	v_pk_add_f32 v[88:89], v[178:179], v[2:3]
	v_pk_add_f32 v[80:81], v[176:177], v[4:5]
	s_waitcnt lgkmcnt(0)
	v_mfma_f32_32x32x16_bf16 v[96:111], v[6:9], v[128:131], v[96:111]
	v_exp_f32_e32 v6, v84
	v_exp_f32_e32 v7, v85
	v_exp_f32_e32 v8, v86
	v_exp_f32_e32 v9, v87
	v_pk_add_f32 v[86:87], v[170:171], v[10:11]
	v_pk_add_f32 v[92:93], v[174:175], v[6:7]
	v_pk_add_f32 v[86:87], v[88:89], v[86:87]
	v_pk_add_f32 v[84:85], v[172:173], v[8:9]
	v_pk_add_f32 v[90:91], v[92:93], v[90:91]
	v_pk_add_f32 v[82:83], v[84:85], v[82:83]
	v_pk_add_f32 v[14:15], v[80:81], v[14:15]
	v_pk_add_f32 v[80:81], v[86:87], v[90:91]
	v_pk_add_f32 v[14:15], v[14:15], v[82:83]
	s_nop 0
	v_pk_add_f32 v[14:15], v[80:81], v[14:15]
	v_cvt_pk_bf16_f32 v80, v178, v179
	v_cvt_pk_bf16_f32 v81, v176, v177
	v_cvt_pk_bf16_f32 v82, v174, v175
	v_cvt_pk_bf16_f32 v83, v172, v173
	v_cvt_pk_bf16_f32 v84, v170, v171
	s_nop 0
	v_pk_add_f32 v[14:15], v[14:15], v[14:15] op_sel:[0,1] op_sel_hi:[1,0]
	v_cvt_pk_bf16_f32 v85, v168, v169
	v_cvt_pk_bf16_f32 v86, v164, v165
	v_cvt_pk_bf16_f32 v87, v162, v163
	v_cvt_pk_bf16_f32 v88, v2, v3
	v_cvt_pk_bf16_f32 v89, v4, v5
	s_nop 0
	v_mov_b32_e32 v0, v14
	s_nop 1
	v_permlane32_swap_b32_e32 v14, v0
	v_cvt_pk_bf16_f32 v90, v6, v7
	v_cvt_pk_bf16_f32 v91, v8, v9
	v_cvt_pk_bf16_f32 v92, v10, v11
	v_cvt_pk_bf16_f32 v93, v12, v13
	v_cvt_pk_bf16_f32 v94, v194, v195
	v_cvt_pk_bf16_f32 v95, v196, v197
	v_lshl_add_u64 v[162:163], v[160:161], 0, s[8:9]
	s_mov_b32 s2, 0xe2e1000
	v_add_co_u32_e32 v2, vcc, s2, v162
	s_mov_b32 s2, 0xe3b1000
	s_nop 0
	v_addc_co_u32_e32 v3, vcc, 0, v163, vcc
	v_add_co_u32_e32 v6, vcc, s2, v162
	v_lshl_add_u64 v[164:165], v[158:159], 0, s[8:9]
	s_nop 0
	v_addc_co_u32_e32 v7, vcc, 0, v163, vcc
	s_mov_b32 s2, 0xe2e0000
	v_add_co_u32_e32 v10, vcc, s2, v164
	global_load_dwordx4 v[2:5], v[2:3], off
	s_nop 0
	global_load_dwordx4 v[6:9], v[6:7], off
	v_addc_co_u32_e32 v11, vcc, 0, v165, vcc
	global_load_dwordx4 v[10:13], v[10:11], off offset:2048
	ds_read_b64_tr_b16 v[168:169], v190 offset:0
	ds_read_b64_tr_b16 v[170:171], v190 offset:0x800
	ds_read_b64_tr_b16 v[172:173], v190 offset:0x1000
	ds_read_b64_tr_b16 v[174:175], v190 offset:0x1800
	ds_read_b64_tr_b16 v[176:177], v190 offset:0x2000
	ds_read_b64_tr_b16 v[178:179], v190 offset:0x2800
	ds_read_b64_tr_b16 v[194:195], v190 offset:0x3000
	ds_read_b64_tr_b16 v[196:197], v190 offset:0x3800
	ds_read_b64_tr_b16 v[232:233], v190 offset:0x200
	ds_read_b64_tr_b16 v[234:235], v190 offset:0xa00
	ds_read_b64_tr_b16 v[236:237], v190 offset:0x1200
	ds_read_b64_tr_b16 v[238:239], v190 offset:0x1a00
	ds_read_b64_tr_b16 v[240:241], v190 offset:0x2200
	ds_read_b64_tr_b16 v[242:243], v190 offset:0x2a00
	ds_read_b64_tr_b16 v[244:245], v190 offset:0x3200
	ds_read_b64_tr_b16 v[246:247], v190 offset:0x3a00
	s_waitcnt lgkmcnt(8)
	s_nop 0
	v_mfma_f32_32x32x16_bf16 v[16:31], v[80:83], v[168:171], v[16:31]
	ds_read_b64_tr_b16 v[168:169], v190 offset:0x400
	ds_read_b64_tr_b16 v[170:171], v190 offset:0xc00
	v_mfma_f32_32x32x16_bf16 v[16:31], v[84:87], v[172:175], v[16:31]
	ds_read_b64_tr_b16 v[172:173], v190 offset:0x1400
	ds_read_b64_tr_b16 v[174:175], v190 offset:0x1c00
	v_mfma_f32_32x32x16_bf16 v[16:31], v[88:91], v[176:179], v[16:31]
	ds_read_b64_tr_b16 v[176:177], v190 offset:0x2400
	ds_read_b64_tr_b16 v[178:179], v190 offset:0x2c00
	v_mfma_f32_32x32x16_bf16 v[16:31], v[92:95], v[194:197], v[16:31]
	ds_read_b64_tr_b16 v[194:195], v190 offset:0x3400
	ds_read_b64_tr_b16 v[196:197], v190 offset:0x3c00
	s_waitcnt lgkmcnt(8)
	v_mfma_f32_32x32x16_bf16 v[32:47], v[80:83], v[232:235], v[32:47]
	ds_read_b64_tr_b16 v[232:233], v190 offset:0x600
	ds_read_b64_tr_b16 v[234:235], v190 offset:0xe00
	v_mfma_f32_32x32x16_bf16 v[32:47], v[84:87], v[236:239], v[32:47]
	ds_read_b64_tr_b16 v[236:237], v190 offset:0x1600
	ds_read_b64_tr_b16 v[238:239], v190 offset:0x1e00
	v_mfma_f32_32x32x16_bf16 v[32:47], v[88:91], v[240:243], v[32:47]
	ds_read_b64_tr_b16 v[240:241], v190 offset:0x2600
	ds_read_b64_tr_b16 v[242:243], v190 offset:0x2e00
	v_mfma_f32_32x32x16_bf16 v[32:47], v[92:95], v[244:247], v[32:47]
	ds_read_b64_tr_b16 v[244:245], v190 offset:0x3600
	ds_read_b64_tr_b16 v[246:247], v190 offset:0x3e00
	s_waitcnt lgkmcnt(8)
	v_mfma_f32_32x32x16_bf16 v[48:63], v[80:83], v[168:171], v[48:63]
	v_mfma_f32_32x32x16_bf16 v[48:63], v[84:87], v[172:175], v[48:63]
	v_mfma_f32_32x32x16_bf16 v[48:63], v[88:91], v[176:179], v[48:63]
	v_mfma_f32_32x32x16_bf16 v[48:63], v[92:95], v[194:197], v[48:63]
	s_waitcnt lgkmcnt(0)
	s_and_b64 vcc, exec, s[18:19]
	s_cbranch_vccnz .Lg3_plain_a
	v_mfma_f32_32x32x16_bf16 v[64:79], v[80:83], v[232:235], v[64:79]
	v_exp_f32_e32 v178, v112
	v_exp_f32_e32 v179, v113
	v_exp_f32_e32 v194, v114
	v_exp_f32_e32 v195, v115
	v_cndmask_b32_e64 v15, 0, 1, s[18:19]
	v_cmp_ne_u32_e64 s[4:5], 1, v15
	s_andn2_b64 vcc, exec, s[18:19]
	v_mfma_f32_32x32x16_bf16 v[64:79], v[84:87], v[236:239], v[64:79]
	v_exp_f32_e32 v196, v116
	v_exp_f32_e32 v197, v117
	v_exp_f32_e32 v198, v118
	v_exp_f32_e32 v199, v119
	v_mfma_f32_32x32x16_bf16 v[64:79], v[88:91], v[240:243], v[64:79]
	v_exp_f32_e32 v210, v120
	v_exp_f32_e32 v211, v121
	v_exp_f32_e32 v212, v122
	v_exp_f32_e32 v213, v123
	v_mfma_f32_32x32x16_bf16 v[64:79], v[92:95], v[244:247], v[64:79]
	v_exp_f32_e32 v214, v124
	v_exp_f32_e32 v215, v125
	v_exp_f32_e32 v216, v126
	v_exp_f32_e32 v217, v127
	s_branch .Lg3_done_a
; template <bool FIRST = false>
; __device__ __forceinline__ void partialSM(f32x16& p0, f32x16& p1, float& m_reg, float& mn, float& alpha, const bool nomax) {
;     ...
;   float pmax = p0[0];
; #pragma unroll
;   for (int r = 1; r < 16; ++r) pmax = fmaxf(pmax, p0[r]);
; #pragma unroll
;   for (int r = 0; r < 16; ++r) pmax = fmaxf(pmax, p1[r]);
;   { auto rr = __builtin_amdgcn_permlane32_swap(__float_as_uint(pmax), __float_as_uint(pmax), false, false); pmax = fmaxf(__uint_as_float(rr[0]), __uint_as_float(rr[1])); }
;   if (FIRST) { m_reg = (__builtin_fabsf(pmax) <= THRL) ? 0.f : pmax; mn = m_reg; alpha = 1.f; }
;   else if (__builtin_expect(__all(pmax - m_reg <= THRL), 1)) { mn = m_reg; alpha = 1.f; }
;   else { mn = fmaxf(m_reg, pmax); alpha = __builtin_amdgcn_exp2f(m_reg - mn); m_reg = mn; }
;   if (__builtin_expect(__any(mn != 0.f), 0)) {
; template <int D0> __device__ __forceinline__ void pv_one(f32x16& od, int vb, bf16x8 pa0, bf16x8 pa1, bf16x8 pa2, bf16x8 pa3) {
;     ...
;   od = __builtin_amdgcn_mfma_f32_32x32x16_bf16(pa0, A128_PK(l0, h0), od, 0, 0, 0);
;   od = __builtin_amdgcn_mfma_f32_32x32x16_bf16(pa1, A128_PK(l1, h1), od, 0, 0, 0);
;   od = __builtin_amdgcn_mfma_f32_32x32x16_bf16(pa2, A128_PK(l2, h2), od, 0, 0, 0);
;   od = __builtin_amdgcn_mfma_f32_32x32x16_bf16(pa3, A128_PK(l3, h3), od, 0, 0, 0);
.Lg3_plain_a:
	v_mfma_f32_32x32x16_bf16 v[64:79], v[80:83], v[232:235], v[64:79]
	v_cndmask_b32_e64 v15, 0, 1, s[18:19]
	v_cmp_ne_u32_e64 s[4:5], 1, v15
	s_andn2_b64 vcc, exec, s[18:19]
	v_mfma_f32_32x32x16_bf16 v[64:79], v[84:87], v[236:239], v[64:79]
	v_mfma_f32_32x32x16_bf16 v[64:79], v[88:91], v[240:243], v[64:79]
	v_mfma_f32_32x32x16_bf16 v[64:79], v[92:95], v[244:247], v[64:79]
.Lg3_done_a:
	s_cbranch_vccnz .LBB0_1113
	v_max_f32_e32 v15, v113, v113
	v_max_f32_e32 v80, v112, v112
	v_max_f32_e32 v15, v80, v15
	v_max3_f32 v15, v15, v114, v115
	v_max3_f32 v15, v15, v116, v117
	v_max3_f32 v15, v15, v118, v119
	v_max3_f32 v15, v15, v120, v121
	v_max3_f32 v15, v15, v122, v123
	v_max3_f32 v15, v15, v124, v125
	v_max3_f32 v15, v15, v126, v127
	v_max3_f32 v15, v15, v96, v97
	v_max3_f32 v15, v15, v98, v99
	v_max3_f32 v15, v15, v100, v101
	v_max3_f32 v15, v15, v102, v103
	v_max3_f32 v15, v15, v104, v105
	v_max3_f32 v15, v15, v106, v107
	v_max3_f32 v15, v15, v108, v109
	v_max3_f32 v15, v15, v110, v111
	v_mov_b32_e32 v80, v15
	s_nop 1
	v_permlane32_swap_b32_e32 v15, v80
	v_max_f32_e32 v80, v80, v80
	v_max_f32_e32 v15, v15, v15
	v_max_f32_e32 v15, v15, v80
	v_sub_f32_e32 v80, v15, v167
	v_cmp_ge_f32_e32 vcc, s74, v80
	s_cmp_eq_u64 vcc, exec
	v_max_f32_e32 v80, v167, v167
	v_max_f32_e32 v15, v80, v15
	s_cselect_b64 s[6:7], -1, 0
	v_cndmask_b32_e64 v168, v15, v167, s[6:7]
	v_cmp_neq_f32_e32 vcc, 0, v168
	s_cbranch_vccnz .LBB0_1132

; #define A128_PK4(P, BASE, OUT) do { u32x4 w = {cvt_pk_bf16(P[BASE + 0], P[BASE + 1]), cvt_pk_bf16(P[BASE + 2], P[BASE + 3]), cvt_pk_bf16(P[BASE + 4], P[BASE + 5]), cvt_pk_bf16(P[BASE + 6], P[BASE + 7])}; \
;     OUT = __builtin_bit_cast(bf16x8, w); } while (0)
; template <bool FIRST = false>
; __device__ __forceinline__ void partialSM(f32x16& p0, f32x16& p1, float& m_reg, float& mn, float& alpha, const bool nomax) {
;     ...
;   for (int r = 0; r < 16; ++r) p0[r] = __builtin_amdgcn_exp2f(p0[r]);
; }
; __device__ __forceinline__ void finishSM(f32x16& p0, f32x16& p1, float alpha, float& l_reg, bf16x8& pa0, bf16x8& pa1, bf16x8& pa2, bf16x8& pa3) {
; #pragma unroll
;   for (int r = 0; r < 16; ++r) p1[r] = __builtin_amdgcn_exp2f(p1[r]);
;   typedef float f32x8_ __attribute__((ext_vector_type(8))); typedef float f32x2_ __attribute__((ext_vector_type(2)));
;   const f32x16 s16_ = p0 + p1; const f32x8_ s8_ = s16_.lo + s16_.hi; const f32x4 s4_ = s8_.lo + s8_.hi; const f32x2_ s2_ = s4_.lo + s4_.hi;
;   float ps = s2_.x + s2_.y;
;   { auto rr = __builtin_amdgcn_permlane32_swap(__float_as_uint(ps), __float_as_uint(ps), false, false); ps = __uint_as_float(rr[0]) + __uint_as_float(rr[1]); }
;   l_reg = l_reg * alpha + ps;
;     ...
;   A128_PK4(p0, 0, pa0); A128_PK4(p0, 8, pa1); A128_PK4(p1, 0, pa2); A128_PK4(p1, 8, pa3);
;     ...
; }
; __device__ __forceinline__ void qkt(f32x16& p0, f32x16& p1, const char* Ks, const bf16x8* qr, int r32, int hi) {
; #pragma unroll
;   for (int i = 0; i < 16; ++i) { p0[i] = 0.f; p1[i] = 0.f; }
; #pragma unroll
;   for (int d0 = 0; d0 < 4; ++d0) { const int cb = (d0 * 16 + hi * 8) * 2;
;     const bf16x8 b0 = *reinterpret_cast<const bf16x8*>(Ks + A128_KSWZ(r32, cb));
;     const bf16x8 b1 = *reinterpret_cast<const bf16x8*>(Ks + A128_KSWZ(32 + r32, cb));
;     p0 = __builtin_amdgcn_mfma_f32_32x32x16_bf16(b0, qr[d0], p0, 0, 0, 0);
;     p1 = __builtin_amdgcn_mfma_f32_32x32x16_bf16(b1, qr[d0], p1, 0, 0, 0); }
.LBB0_1119:
	s_and_b64 vcc, exec, s[4:5]
	s_cbranch_vccnz .Lskip_exps_a
	v_exp_f32_e32 v178, v112
	v_exp_f32_e32 v179, v113
	v_exp_f32_e32 v194, v114
	v_exp_f32_e32 v195, v115
	v_exp_f32_e32 v196, v116
	v_exp_f32_e32 v197, v117
	v_exp_f32_e32 v198, v118
	v_exp_f32_e32 v199, v119
	v_exp_f32_e32 v210, v120
	v_exp_f32_e32 v211, v121
	v_exp_f32_e32 v212, v122
	v_exp_f32_e32 v213, v123
	v_exp_f32_e32 v214, v124
	v_exp_f32_e32 v215, v125
	v_exp_f32_e32 v216, v126
	v_exp_f32_e32 v217, v127
.Lskip_exps_a:
	s_waitcnt lgkmcnt(0)
	s_barrier
	ds_read_b128 v[80:83], v204 offset:32768
	ds_read_b128 v[84:87], v204 offset:36864
	ds_read_b128 v[170:173], v205 offset:32768
	ds_read_b128 v[174:177], v205 offset:36864
	ds_read_b128 v[232:235], v192 offset:32768
	ds_read_b128 v[236:239], v192 offset:36864
	v_exp_f32_e32 v104, v104
	v_exp_f32_e32 v105, v105
	s_waitcnt lgkmcnt(5)
	v_mfma_f32_32x32x16_bf16 v[112:127], v[80:83], v[140:143], 0
	v_exp_f32_e32 v106, v106
	v_exp_f32_e32 v107, v107
	v_exp_f32_e32 v226, v108
	v_exp_f32_e32 v227, v109
	v_exp_f32_e32 v228, v110
	v_exp_f32_e32 v229, v111
	v_pk_add_f32 v[108:109], v[104:105], v[210:211]
	s_waitcnt lgkmcnt(4)
	v_mfma_f32_32x32x16_bf16 v[80:95], v[84:87], v[140:143], 0
	v_add_f32_e64 v166, v226, v214
	v_add_f32_e64 v167, v227, v215
	s_waitcnt lgkmcnt(3)
	v_mfma_f32_32x32x16_bf16 v[112:127], v[170:173], v[136:139], v[112:127]
	s_waitcnt lgkmcnt(2)
	v_mfma_f32_32x32x16_bf16 v[80:95], v[174:177], v[136:139], v[80:95]
	ds_read_b128 v[170:173], v193 offset:32768
	ds_read_b128 v[174:177], v193 offset:36864
	s_waitcnt lgkmcnt(3)
	v_mfma_f32_32x32x16_bf16 v[112:127], v[232:235], v[132:135], v[112:127]
	s_waitcnt lgkmcnt(2)
	v_mfma_f32_32x32x16_bf16 v[80:95], v[236:239], v[132:135], v[80:95]
	s_waitcnt lgkmcnt(1)
	v_mfma_f32_32x32x16_bf16 v[112:127], v[170:173], v[128:131], v[112:127]
	v_exp_f32_e32 v170, v96
	v_exp_f32_e32 v171, v97
	v_exp_f32_e32 v172, v98
	v_exp_f32_e32 v173, v99
	v_pk_add_f32 v[96:97], v[106:107], v[212:213]
	v_pk_add_f32 v[110:111], v[170:171], v[178:179]
	v_pk_add_f32 v[98:99], v[172:173], v[194:195]
	s_waitcnt lgkmcnt(0)
	v_mfma_f32_32x32x16_bf16 v[80:95], v[174:177], v[128:131], v[80:95]
	v_exp_f32_e32 v174, v100
	v_exp_f32_e32 v175, v101
	v_exp_f32_e32 v176, v102
	v_exp_f32_e32 v177, v103
	v_pk_add_f32 v[100:101], v[228:229], v[216:217]
	v_pk_add_f32 v[208:209], v[174:175], v[196:197]
	v_pk_add_f32 v[108:109], v[110:111], v[108:109]
	v_pk_add_f32 v[102:103], v[176:177], v[198:199]
	v_pk_add_f32 v[166:167], v[208:209], v[166:167]
	v_pk_add_f32 v[100:101], v[102:103], v[100:101]
	v_pk_add_f32 v[96:97], v[98:99], v[96:97]
	v_pk_add_f32 v[98:99], v[108:109], v[166:167]
	v_pk_add_f32 v[96:97], v[96:97], v[100:101]
	s_nop 0
	v_pk_add_f32 v[96:97], v[98:99], v[96:97]
	s_nop 0
	v_pk_add_f32 v[166:167], v[96:97], v[96:97] op_sel:[0,1] op_sel_hi:[1,0]
	v_cvt_pk_bf16_f32 v96, v178, v179
	v_cvt_pk_bf16_f32 v97, v194, v195
	v_cvt_pk_bf16_f32 v98, v196, v197
	v_cvt_pk_bf16_f32 v99, v198, v199
	v_cvt_pk_bf16_f32 v100, v210, v211
	s_nop 0
	v_mov_b32_e32 v208, v166
	s_nop 1
	v_permlane32_swap_b32_e32 v166, v208
	v_cvt_pk_bf16_f32 v101, v212, v213
	v_cvt_pk_bf16_f32 v102, v214, v215
	v_cvt_pk_bf16_f32 v103, v216, v217
	v_cvt_pk_bf16_f32 v108, v170, v171
	v_cvt_pk_bf16_f32 v109, v172, v173
	v_cvt_pk_bf16_f32 v110, v174, v175
	v_cvt_pk_bf16_f32 v111, v176, v177
	v_cvt_pk_bf16_f32 v104, v104, v105
	v_cvt_pk_bf16_f32 v105, v106, v107
	v_cvt_pk_bf16_f32 v106, v226, v227
	v_cvt_pk_bf16_f32 v107, v228, v229
	s_cmp_ge_u32 s38, s27
	s_cselect_b64 s[2:3], -1, 0
	s_and_b64 vcc, exec, s[2:3]
	s_cbranch_vccnz .Latt_noload_a
	v_add_co_u32_e32 v144, vcc, 0xe481000, v162
	s_nop 1
	v_addc_co_u32_e32 v145, vcc, 0, v163, vcc
	v_add_co_u32_e32 v146, vcc, 0xe551000, v162
	s_nop 1
	v_addc_co_u32_e32 v147, vcc, 0, v163, vcc
	global_load_dwordx4 v[152:155], v[144:145], off
	global_load_dwordx4 v[148:151], v[146:147], off
	v_add_co_u32_e32 v144, vcc, 0xe480000, v164
	s_nop 1
	v_addc_co_u32_e32 v145, vcc, 0, v165, vcc
	global_load_dwordx4 v[144:147], v[144:145], off offset:2048
; template <bool FIRST = false>
; __device__ __forceinline__ void partialSM(f32x16& p0, f32x16& p1, float& m_reg, float& mn, float& alpha, const bool nomax) {
;   if (nomax) { mn = 0.f; alpha = 1.f;
; #pragma unroll
;     for (int r = 0; r < 16; ++r) p0[r] = __builtin_amdgcn_exp2f(p0[r]);
;     return; }
;   float pmax = p0[0];
; #pragma unroll
;   for (int r = 1; r < 16; ++r) pmax = fmaxf(pmax, p0[r]);
; #pragma unroll
;   for (int r = 0; r < 16; ++r) pmax = fmaxf(pmax, p1[r]);
;   { auto rr = __builtin_amdgcn_permlane32_swap(__float_as_uint(pmax), __float_as_uint(pmax), false, false); pmax = fmaxf(__uint_as_float(rr[0]), __uint_as_float(rr[1])); }
;   if (FIRST) { m_reg = (__builtin_fabsf(pmax) <= THRL) ? 0.f : pmax; mn = m_reg; alpha = 1.f; }
;   else if (__builtin_expect(__all(pmax - m_reg <= THRL), 1)) { mn = m_reg; alpha = 1.f; }
;   else { mn = fmaxf(m_reg, pmax); alpha = __builtin_amdgcn_exp2f(m_reg - mn); m_reg = mn; }
;   if (__builtin_expect(__any(mn != 0.f), 0)) {
; #pragma unroll
;     for (int r = 0; r < 16; ++r) { p0[r] = p0[r] - mn; p1[r] = p1[r] - mn; } }
; #pragma unroll
;   for (int r = 0; r < 16; ++r) p0[r] = __builtin_amdgcn_exp2f(p0[r]);
; }
; __device__ __forceinline__ void finishSM(f32x16& p0, f32x16& p1, float alpha, float& l_reg, bf16x8& pa0, bf16x8& pa1, bf16x8& pa2, bf16x8& pa3) {
; #pragma unroll
;   for (int r = 0; r < 16; ++r) p1[r] = __builtin_amdgcn_exp2f(p1[r]);
;   typedef float f32x8_ __attribute__((ext_vector_type(8))); typedef float f32x2_ __attribute__((ext_vector_type(2)));
;   const f32x16 s16_ = p0 + p1; const f32x8_ s8_ = s16_.lo + s16_.hi; const f32x4 s4_ = s8_.lo + s8_.hi; const f32x2_ s2_ = s4_.lo + s4_.hi;
;   float ps = s2_.x + s2_.y;
;   { auto rr = __builtin_amdgcn_permlane32_swap(__float_as_uint(ps), __float_as_uint(ps), false, false); ps = __uint_as_float(rr[0]) + __uint_as_float(rr[1]); }
;   l_reg = l_reg * alpha + ps;
;     ...
;   A128_PK4(p0, 0, pa0); A128_PK4(p0, 8, pa1); A128_PK4(p1, 0, pa2); A128_PK4(p1, 8, pa3);
;     ...
; }
; __device__ __forceinline__ void qkt(f32x16& p0, f32x16& p1, const char* Ks, const bf16x8* qr, int r32, int hi) {
; #pragma unroll
;   for (int i = 0; i < 16; ++i) { p0[i] = 0.f; p1[i] = 0.f; }
; #pragma unroll
;   for (int d0 = 0; d0 < 4; ++d0) { const int cb = (d0 * 16 + hi * 8) * 2;
;     const bf16x8 b0 = *reinterpret_cast<const bf16x8*>(Ks + A128_KSWZ(r32, cb));
.LBB0_1121:
	ds_read_b64_tr_b16 v[162:163], v189 offset:0
	ds_read_b64_tr_b16 v[164:165], v189 offset:0x800
	ds_read_b64_tr_b16 v[170:171], v189 offset:0x1000
	ds_read_b64_tr_b16 v[172:173], v189 offset:0x1800
	ds_read_b64_tr_b16 v[174:175], v189 offset:0x2000
	ds_read_b64_tr_b16 v[176:177], v189 offset:0x2800
	ds_read_b64_tr_b16 v[194:195], v189 offset:0x3000
	ds_read_b64_tr_b16 v[196:197], v189 offset:0x3800
	ds_read_b64_tr_b16 v[232:233], v189 offset:0x200
	ds_read_b64_tr_b16 v[234:235], v189 offset:0xa00
	ds_read_b64_tr_b16 v[236:237], v189 offset:0x1200
	ds_read_b64_tr_b16 v[238:239], v189 offset:0x1a00
	ds_read_b64_tr_b16 v[240:241], v189 offset:0x2200
	ds_read_b64_tr_b16 v[242:243], v189 offset:0x2a00
	ds_read_b64_tr_b16 v[244:245], v189 offset:0x3200
	ds_read_b64_tr_b16 v[246:247], v189 offset:0x3a00
	s_waitcnt lgkmcnt(8)
	s_nop 0
	v_mfma_f32_32x32x16_bf16 v[16:31], v[96:99], v[162:165], v[16:31]
	ds_read_b64_tr_b16 v[162:163], v189 offset:0x400
	ds_read_b64_tr_b16 v[164:165], v189 offset:0xc00
	v_mfma_f32_32x32x16_bf16 v[16:31], v[100:103], v[170:173], v[16:31]
	ds_read_b64_tr_b16 v[170:171], v189 offset:0x1400
	ds_read_b64_tr_b16 v[172:173], v189 offset:0x1c00
	v_mfma_f32_32x32x16_bf16 v[16:31], v[108:111], v[174:177], v[16:31]
	ds_read_b64_tr_b16 v[174:175], v189 offset:0x2400
	ds_read_b64_tr_b16 v[176:177], v189 offset:0x2c00
	v_mfma_f32_32x32x16_bf16 v[16:31], v[104:107], v[194:197], v[16:31]
	ds_read_b64_tr_b16 v[194:195], v189 offset:0x3400
	ds_read_b64_tr_b16 v[196:197], v189 offset:0x3c00
	s_waitcnt lgkmcnt(8)
	v_mfma_f32_32x32x16_bf16 v[32:47], v[96:99], v[232:235], v[32:47]
	ds_read_b64_tr_b16 v[232:233], v189 offset:0x600
	ds_read_b64_tr_b16 v[234:235], v189 offset:0xe00
	v_mfma_f32_32x32x16_bf16 v[32:47], v[100:103], v[236:239], v[32:47]
	ds_read_b64_tr_b16 v[236:237], v189 offset:0x1600
	ds_read_b64_tr_b16 v[238:239], v189 offset:0x1e00
	v_mfma_f32_32x32x16_bf16 v[32:47], v[108:111], v[240:243], v[32:47]
	ds_read_b64_tr_b16 v[240:241], v189 offset:0x2600
	ds_read_b64_tr_b16 v[242:243], v189 offset:0x2e00
	v_mfma_f32_32x32x16_bf16 v[32:47], v[104:107], v[244:247], v[32:47]
	ds_read_b64_tr_b16 v[244:245], v189 offset:0x3600
	ds_read_b64_tr_b16 v[246:247], v189 offset:0x3e00
	s_waitcnt lgkmcnt(8)
	v_mfma_f32_32x32x16_bf16 v[48:63], v[96:99], v[162:165], v[48:63]
	v_mfma_f32_32x32x16_bf16 v[48:63], v[100:103], v[170:173], v[48:63]
	v_mfma_f32_32x32x16_bf16 v[48:63], v[108:111], v[174:177], v[48:63]
	v_mfma_f32_32x32x16_bf16 v[48:63], v[104:107], v[194:197], v[48:63]
	s_waitcnt lgkmcnt(0)
	s_and_b64 vcc, exec, s[4:5]
	s_cbranch_vccz .Lg3_plain_b
	v_mfma_f32_32x32x16_bf16 v[64:79], v[96:99], v[232:235], v[64:79]
	v_exp_f32_e32 v178, v112
	v_exp_f32_e32 v179, v113
	v_exp_f32_e32 v176, v114
	v_exp_f32_e32 v177, v115
	v_mov_b32_e32 v15, 1.0
	s_and_b64 vcc, exec, s[4:5]
	v_mfma_f32_32x32x16_bf16 v[64:79], v[100:103], v[236:239], v[64:79]
	v_exp_f32_e32 v174, v116
	v_exp_f32_e32 v175, v117
	v_exp_f32_e32 v172, v118
	v_exp_f32_e32 v173, v119
	v_mfma_f32_32x32x16_bf16 v[64:79], v[108:111], v[240:243], v[64:79]
	v_exp_f32_e32 v170, v120
	v_exp_f32_e32 v171, v121
	v_exp_f32_e32 v168, v122
	v_exp_f32_e32 v169, v123
	v_mfma_f32_32x32x16_bf16 v[64:79], v[104:107], v[244:247], v[64:79]
	v_exp_f32_e32 v164, v124
	v_exp_f32_e32 v165, v125
	v_exp_f32_e32 v162, v126
	v_exp_f32_e32 v163, v127
	s_branch .Lg3_done_b
.Lg3_plain_b:
	v_mfma_f32_32x32x16_bf16 v[64:79], v[96:99], v[232:235], v[64:79]
	v_mov_b32_e32 v15, 1.0
	s_and_b64 vcc, exec, s[4:5]
	v_mfma_f32_32x32x16_bf16 v[64:79], v[100:103], v[236:239], v[64:79]
	v_mfma_f32_32x32x16_bf16 v[64:79], v[108:111], v[240:243], v[64:79]
	v_mfma_f32_32x32x16_bf16 v[64:79], v[104:107], v[244:247], v[64:79]
.Lg3_done_b:
	s_cbranch_vccnz .LBB0_1124
	v_max_f32_e32 v15, v113, v113
	v_max_f32_e32 v96, v112, v112
	v_max_f32_e32 v15, v96, v15
	v_max3_f32 v15, v15, v114, v115
	v_max3_f32 v15, v15, v116, v117
	v_max3_f32 v15, v15, v118, v119
	v_max3_f32 v15, v15, v120, v121
	v_max3_f32 v15, v15, v122, v123
	v_max3_f32 v15, v15, v124, v125
	v_max3_f32 v15, v15, v126, v127
	v_max3_f32 v15, v15, v80, v81
	v_max3_f32 v15, v15, v82, v83
	v_max3_f32 v15, v15, v84, v85
	v_max3_f32 v15, v15, v86, v87
	v_max3_f32 v15, v15, v88, v89
	v_max3_f32 v15, v15, v90, v91
	v_max3_f32 v15, v15, v92, v93
	v_max3_f32 v15, v15, v94, v95
	v_mov_b32_e32 v96, v15
	s_nop 1
	v_permlane32_swap_b32_e32 v15, v96
	v_max_f32_e32 v96, v96, v96
	v_max_f32_e32 v15, v15, v15
	v_max_f32_e32 v15, v15, v96
	v_sub_f32_e32 v96, v15, v168
	v_cmp_ge_f32_e32 vcc, s74, v96
	s_cmp_eq_u64 vcc, exec
	v_max_f32_e32 v96, v168, v168
	v_max_f32_e32 v15, v96, v15
	s_cselect_b64 s[6:7], -1, 0
	v_cndmask_b32_e64 v167, v15, v168, s[6:7]
	v_cmp_neq_f32_e32 vcc, 0, v167
	s_cbranch_vccnz .LBB0_1133

; template <bool FIRST = false>
; __device__ __forceinline__ void partialSM(f32x16& p0, f32x16& p1, float& m_reg, float& mn, float& alpha, const bool nomax) {
;     ...
;   for (int r = 0; r < 16; ++r) p0[r] = __builtin_amdgcn_exp2f(p0[r]);
; }
; __device__ __forceinline__ void finishSM(f32x16& p0, f32x16& p1, float alpha, float& l_reg, bf16x8& pa0, bf16x8& pa1, bf16x8& pa2, bf16x8& pa3) {
; #pragma unroll
;   for (int r = 0; r < 16; ++r) p1[r] = __builtin_amdgcn_exp2f(p1[r]);
;   typedef float f32x8_ __attribute__((ext_vector_type(8))); typedef float f32x2_ __attribute__((ext_vector_type(2)));
;   const f32x16 s16_ = p0 + p1; const f32x8_ s8_ = s16_.lo + s16_.hi; const f32x4 s4_ = s8_.lo + s8_.hi; const f32x2_ s2_ = s4_.lo + s4_.hi;
;   float ps = s2_.x + s2_.y;
;   { auto rr = __builtin_amdgcn_permlane32_swap(__float_as_uint(ps), __float_as_uint(ps), false, false); ps = __uint_as_float(rr[0]) + __uint_as_float(rr[1]); }
;   l_reg = l_reg * alpha + ps;
.LBB0_1130:
	s_and_b64 vcc, exec, s[4:5]
	s_cbranch_vccnz .Lskip_exps_b
	v_exp_f32_e32 v178, v112
	v_exp_f32_e32 v179, v113
	v_exp_f32_e32 v176, v114
	v_exp_f32_e32 v177, v115
	v_exp_f32_e32 v174, v116
	v_exp_f32_e32 v175, v117
	v_exp_f32_e32 v172, v118
	v_exp_f32_e32 v173, v119
	v_exp_f32_e32 v170, v120
	v_exp_f32_e32 v171, v121
	v_exp_f32_e32 v168, v122
	v_exp_f32_e32 v169, v123
	v_exp_f32_e32 v164, v124
	v_exp_f32_e32 v165, v125
	v_exp_f32_e32 v162, v126
	v_exp_f32_e32 v163, v127
.Lskip_exps_b:
	v_add_f32_e32 v0, v14, v0
	v_fmac_f32_e32 v0, v206, v186
	v_add_f32_e32 v186, v166, v208
	v_fmac_f32_e32 v186, v0, v207
	v_lshl_add_u64 v[158:159], v[158:159], 0, s[96:97]
	v_lshl_add_u64 v[160:161], v[160:161], 0, s[96:97]
	s_add_i32 s38, s38, 2
	s_and_b64 vcc, exec, s[2:3]
	s_waitcnt lgkmcnt(0)
	s_barrier
	s_cbranch_vccnz .LBB0_1134
	v_mov_b32_e32 v206, v15
	s_branch .LBB0_1110
